# variant: static priority raise given to the leading wave group instead of the trailing one
# baseline (speedup 1.0000x reference)
.LBB0_213:
	s_ashr_i32 s45, s44, 31
	s_lshl_b64 s[2:3], s[44:45], 19
	s_add_u32 s46, s18, s2
	s_addc_u32 s47, s19, s3
	s_and_b64 s[2:3], s[38:39], exec
	s_cselect_b32 s2, s47, s53
	s_cselect_b32 s3, s46, s52
	s_ashr_i32 s43, s42, 31
	s_lshl_b64 s[24:25], s[42:43], 19
	s_add_u32 s48, s97, s24
	v_readlane_b32 s13, v255, 8
	s_addc_u32 s49, s13, s25
	s_and_b64 s[24:25], s[38:39], exec
	s_cselect_b32 s13, s49, s71
	s_cselect_b32 s16, s48, s70
	s_add_u32 s30, s52, 0x40080
	s_addc_u32 s31, s53, 0
	s_add_u32 s24, s70, 0x100
	s_addc_u32 s25, s71, 0
	s_mov_b32 s26, -2
	v_mov_b64_e32 v[2:3], 0
	v_mov_b64_e32 v[4:5], 0
	v_mov_b64_e32 v[6:7], 0
	v_mov_b64_e32 v[8:9], 0
	v_mov_b64_e32 v[10:11], 0
	v_mov_b64_e32 v[12:13], 0
	v_mov_b64_e32 v[14:15], 0
	v_mov_b64_e32 v[16:17], 0
	v_mov_b64_e32 v[18:19], 0
	v_mov_b64_e32 v[20:21], 0
	v_mov_b64_e32 v[22:23], 0
	v_mov_b64_e32 v[24:25], 0
	v_mov_b64_e32 v[26:27], 0
	v_mov_b64_e32 v[28:29], 0
	v_mov_b64_e32 v[30:31], 0
	v_mov_b64_e32 v[32:33], 0
	v_mov_b64_e32 v[34:35], 0
	v_mov_b64_e32 v[36:37], 0
	v_mov_b64_e32 v[38:39], 0
	v_mov_b64_e32 v[40:41], 0
	v_mov_b64_e32 v[42:43], 0
	v_mov_b64_e32 v[44:45], 0
	v_mov_b64_e32 v[46:47], 0
	v_mov_b64_e32 v[48:49], 0
	v_mov_b64_e32 v[50:51], 0
	v_mov_b64_e32 v[52:53], 0
	v_mov_b64_e32 v[54:55], 0
	v_mov_b64_e32 v[56:57], 0
	v_mov_b64_e32 v[58:59], 0
	v_mov_b64_e32 v[60:61], 0
	v_mov_b64_e32 v[62:63], 0
	v_mov_b64_e32 v[64:65], 0
	v_mov_b64_e32 v[66:67], 0
	v_mov_b64_e32 v[68:69], 0
	v_mov_b64_e32 v[70:71], 0
	v_mov_b64_e32 v[72:73], 0
	v_mov_b64_e32 v[74:75], 0
	v_mov_b64_e32 v[76:77], 0
	v_mov_b64_e32 v[78:79], 0
	v_mov_b64_e32 v[80:81], 0
	v_mov_b64_e32 v[82:83], 0
	v_mov_b64_e32 v[84:85], 0
	v_mov_b64_e32 v[86:87], 0
	v_mov_b64_e32 v[88:89], 0
	v_mov_b64_e32 v[90:91], 0
	v_mov_b64_e32 v[92:93], 0
	v_mov_b64_e32 v[94:95], 0
	v_mov_b64_e32 v[96:97], 0
	v_mov_b64_e32 v[98:99], 0
	v_mov_b64_e32 v[100:101], 0
	v_mov_b64_e32 v[102:103], 0
	v_mov_b64_e32 v[104:105], 0
	v_mov_b64_e32 v[106:107], 0
	v_mov_b64_e32 v[108:109], 0
	v_mov_b64_e32 v[110:111], 0
	v_mov_b64_e32 v[112:113], 0
	v_mov_b64_e32 v[114:115], 0
	v_mov_b64_e32 v[116:117], 0
	v_mov_b64_e32 v[118:119], 0
	v_mov_b64_e32 v[120:121], 0
	v_mov_b64_e32 v[122:123], 0
	v_mov_b64_e32 v[124:125], 0
	v_mov_b64_e32 v[126:127], 0
	v_mov_b64_e32 v[128:129], 0
	s_cmp_lt_u32 s32, 0x100
	s_cbranch_scc0 .Lsprio_0
	s_setprio 1

.LBB0_694:
	s_ashr_i32 s45, s44, 31
	s_lshl_b64 s[24:25], s[44:45], 19
	s_add_u32 s46, s17, s24
	s_addc_u32 s47, s18, s25
	s_and_b64 s[24:25], s[42:43], exec
	s_cselect_b32 s3, s47, s13
	s_cselect_b32 s16, s46, s12
	s_ashr_i32 s35, s34, 31
	s_lshl_b64 s[24:25], s[34:35], 19
	s_add_u32 s48, s19, s24
	s_addc_u32 s49, s29, s25
	s_and_b64 s[24:25], s[42:43], exec
	s_cselect_b32 s24, s49, s31
	s_cselect_b32 s25, s48, s30
	s_add_u32 s12, s12, 0x40080
	s_addc_u32 s13, s13, 0
	s_add_u32 s26, s30, 0x100
	s_addc_u32 s28, s31, 0
	s_mov_b32 s35, -2
	s_waitcnt vmcnt(0)
	v_mov_b64_e32 v[2:3], 0
	v_mov_b64_e32 v[4:5], 0
	v_mov_b64_e32 v[6:7], 0
	v_mov_b64_e32 v[8:9], 0
	v_mov_b64_e32 v[10:11], 0
	v_mov_b64_e32 v[12:13], 0
	v_mov_b64_e32 v[14:15], 0
	v_mov_b64_e32 v[16:17], 0
	v_mov_b64_e32 v[18:19], 0
	v_mov_b64_e32 v[20:21], 0
	v_mov_b64_e32 v[22:23], 0
	v_mov_b64_e32 v[24:25], 0
	v_mov_b64_e32 v[26:27], 0
	v_mov_b64_e32 v[28:29], 0
	v_mov_b64_e32 v[30:31], 0
	v_mov_b64_e32 v[32:33], 0
	v_mov_b64_e32 v[34:35], 0
	v_mov_b64_e32 v[36:37], 0
	v_mov_b64_e32 v[38:39], 0
	v_mov_b64_e32 v[40:41], 0
	v_mov_b64_e32 v[42:43], 0
	v_mov_b64_e32 v[44:45], 0
	v_mov_b64_e32 v[46:47], 0
	v_mov_b64_e32 v[48:49], 0
	v_mov_b64_e32 v[50:51], 0
	v_mov_b64_e32 v[52:53], 0
	v_mov_b64_e32 v[54:55], 0
	v_mov_b64_e32 v[56:57], 0
	v_mov_b64_e32 v[58:59], 0
	v_mov_b64_e32 v[60:61], 0
	v_mov_b64_e32 v[62:63], 0
	v_mov_b64_e32 v[64:65], 0
	v_mov_b64_e32 v[66:67], 0
	v_mov_b64_e32 v[68:69], 0
	v_mov_b64_e32 v[70:71], 0
	v_mov_b64_e32 v[72:73], 0
	v_mov_b64_e32 v[74:75], 0
	v_mov_b64_e32 v[76:77], 0
	v_mov_b64_e32 v[78:79], 0
	v_mov_b64_e32 v[80:81], 0
	v_mov_b64_e32 v[82:83], 0
	v_mov_b64_e32 v[84:85], 0
	v_mov_b64_e32 v[86:87], 0
	v_mov_b64_e32 v[88:89], 0
	v_mov_b64_e32 v[90:91], 0
	v_mov_b64_e32 v[92:93], 0
	v_mov_b64_e32 v[94:95], 0
	v_mov_b64_e32 v[96:97], 0
	v_mov_b64_e32 v[98:99], 0
	v_mov_b64_e32 v[100:101], 0
	v_mov_b64_e32 v[102:103], 0
	v_mov_b64_e32 v[104:105], 0
	v_mov_b64_e32 v[106:107], 0
	v_mov_b64_e32 v[108:109], 0
	v_mov_b64_e32 v[110:111], 0
	v_mov_b64_e32 v[112:113], 0
	v_mov_b64_e32 v[114:115], 0
	v_mov_b64_e32 v[116:117], 0
	v_mov_b64_e32 v[118:119], 0
	v_mov_b64_e32 v[120:121], 0
	v_mov_b64_e32 v[122:123], 0
	v_mov_b64_e32 v[124:125], 0
	v_mov_b64_e32 v[126:127], 0
	v_mov_b64_e32 v[128:129], 0
	s_cmp_lt_u32 s32, 0x100
	s_cbranch_scc0 .Lsprio_1
	s_setprio 1

.LBB0_791:
	s_ashr_i32 s15, s14, 31
	s_lshl_b64 s[20:21], s[14:15], 19
	s_add_u32 s20, s2, s20
	s_addc_u32 s21, s3, s21
	s_and_b64 s[30:31], s[4:5], exec
	s_cselect_b32 s15, s21, s35
	s_cselect_b32 s46, s20, s34
	s_ashr_i32 s13, s12, 31
	s_lshl_b64 s[30:31], s[12:13], 19
	s_add_u32 s30, s16, s30
	s_addc_u32 s31, s17, s31
	s_and_b64 s[40:41], s[4:5], exec
	s_cselect_b32 s13, s31, s37
	s_cselect_b32 s47, s30, s36
	s_add_u32 s34, s34, 0x40080
	s_addc_u32 s35, s35, 0
	s_add_u32 s48, s36, 0x100
	s_addc_u32 s49, s37, 0
	s_mov_b32 s50, -2
	v_mov_b64_e32 v[2:3], 0
	v_mov_b64_e32 v[4:5], 0
	v_mov_b64_e32 v[6:7], 0
	v_mov_b64_e32 v[8:9], 0
	v_mov_b64_e32 v[10:11], 0
	v_mov_b64_e32 v[12:13], 0
	v_mov_b64_e32 v[14:15], 0
	v_mov_b64_e32 v[16:17], 0
	v_mov_b64_e32 v[18:19], 0
	v_mov_b64_e32 v[20:21], 0
	v_mov_b64_e32 v[22:23], 0
	v_mov_b64_e32 v[24:25], 0
	v_mov_b64_e32 v[26:27], 0
	v_mov_b64_e32 v[28:29], 0
	v_mov_b64_e32 v[30:31], 0
	v_mov_b64_e32 v[32:33], 0
	v_mov_b64_e32 v[34:35], 0
	v_mov_b64_e32 v[36:37], 0
	v_mov_b64_e32 v[38:39], 0
	v_mov_b64_e32 v[40:41], 0
	v_mov_b64_e32 v[42:43], 0
	v_mov_b64_e32 v[44:45], 0
	v_mov_b64_e32 v[46:47], 0
	v_mov_b64_e32 v[48:49], 0
	v_mov_b64_e32 v[50:51], 0
	v_mov_b64_e32 v[52:53], 0
	v_mov_b64_e32 v[54:55], 0
	v_mov_b64_e32 v[56:57], 0
	v_mov_b64_e32 v[58:59], 0
	v_mov_b64_e32 v[60:61], 0
	v_mov_b64_e32 v[62:63], 0
	v_mov_b64_e32 v[64:65], 0
	v_mov_b64_e32 v[66:67], 0
	v_mov_b64_e32 v[68:69], 0
	v_mov_b64_e32 v[70:71], 0
	v_mov_b64_e32 v[72:73], 0
	v_mov_b64_e32 v[74:75], 0
	v_mov_b64_e32 v[76:77], 0
	v_mov_b64_e32 v[78:79], 0
	v_mov_b64_e32 v[80:81], 0
	v_mov_b64_e32 v[82:83], 0
	v_mov_b64_e32 v[84:85], 0
	v_mov_b64_e32 v[86:87], 0
	v_mov_b64_e32 v[88:89], 0
	v_mov_b64_e32 v[90:91], 0
	v_mov_b64_e32 v[92:93], 0
	v_mov_b64_e32 v[94:95], 0
	v_mov_b64_e32 v[96:97], 0
	v_mov_b64_e32 v[98:99], 0
	v_mov_b64_e32 v[100:101], 0
	v_mov_b64_e32 v[102:103], 0
	v_mov_b64_e32 v[104:105], 0
	v_mov_b64_e32 v[106:107], 0
	v_mov_b64_e32 v[108:109], 0
	v_mov_b64_e32 v[110:111], 0
	v_mov_b64_e32 v[112:113], 0
	v_mov_b64_e32 v[114:115], 0
	v_mov_b64_e32 v[116:117], 0
	v_mov_b64_e32 v[118:119], 0
	v_mov_b64_e32 v[120:121], 0
	v_mov_b64_e32 v[122:123], 0
	v_mov_b64_e32 v[124:125], 0
	v_mov_b64_e32 v[126:127], 0
	v_mov_b64_e32 v[128:129], 0
	s_cmp_lt_u32 s32, 0x100
	s_cbranch_scc0 .Lsprio_2
	s_setprio 1

.LBB0_863:
	s_ashr_i32 s45, s44, 31
	s_lshl_b64 s[24:25], s[44:45], 21
	s_add_u32 s46, s17, s24
	s_addc_u32 s47, s18, s25
	s_and_b64 s[24:25], s[42:43], exec
	s_cselect_b32 s3, s47, s13
	s_cselect_b32 s16, s46, s12
	s_ashr_i32 s35, s34, 31
	s_lshl_b64 s[24:25], s[34:35], 21
	s_add_u32 s48, s19, s24
	s_addc_u32 s49, s29, s25
	s_and_b64 s[24:25], s[42:43], exec
	s_cselect_b32 s24, s49, s31
	s_cselect_b32 s25, s48, s30
	s_add_u32 s12, s12, 0x100080
	s_addc_u32 s13, s13, 0
	s_add_u32 s26, s30, 0x100
	s_addc_u32 s28, s31, 0
	s_mov_b32 s35, -2
	v_mov_b64_e32 v[2:3], 0
	v_mov_b64_e32 v[4:5], 0
	v_mov_b64_e32 v[6:7], 0
	v_mov_b64_e32 v[8:9], 0
	v_mov_b64_e32 v[10:11], 0
	v_mov_b64_e32 v[12:13], 0
	v_mov_b64_e32 v[14:15], 0
	v_mov_b64_e32 v[16:17], 0
	v_mov_b64_e32 v[18:19], 0
	v_mov_b64_e32 v[20:21], 0
	v_mov_b64_e32 v[22:23], 0
	v_mov_b64_e32 v[24:25], 0
	v_mov_b64_e32 v[26:27], 0
	v_mov_b64_e32 v[28:29], 0
	v_mov_b64_e32 v[30:31], 0
	v_mov_b64_e32 v[32:33], 0
	v_mov_b64_e32 v[34:35], 0
	v_mov_b64_e32 v[36:37], 0
	v_mov_b64_e32 v[38:39], 0
	v_mov_b64_e32 v[40:41], 0
	v_mov_b64_e32 v[42:43], 0
	v_mov_b64_e32 v[44:45], 0
	v_mov_b64_e32 v[46:47], 0
	v_mov_b64_e32 v[48:49], 0
	v_mov_b64_e32 v[50:51], 0
	v_mov_b64_e32 v[52:53], 0
	v_mov_b64_e32 v[54:55], 0
	v_mov_b64_e32 v[56:57], 0
	v_mov_b64_e32 v[58:59], 0
	v_mov_b64_e32 v[60:61], 0
	v_mov_b64_e32 v[62:63], 0
	v_mov_b64_e32 v[64:65], 0
	v_mov_b64_e32 v[66:67], 0
	v_mov_b64_e32 v[68:69], 0
	v_mov_b64_e32 v[70:71], 0
	v_mov_b64_e32 v[72:73], 0
	v_mov_b64_e32 v[74:75], 0
	v_mov_b64_e32 v[76:77], 0
	v_mov_b64_e32 v[78:79], 0
	v_mov_b64_e32 v[80:81], 0
	v_mov_b64_e32 v[82:83], 0
	v_mov_b64_e32 v[84:85], 0
	v_mov_b64_e32 v[86:87], 0
	v_mov_b64_e32 v[88:89], 0
	v_mov_b64_e32 v[90:91], 0
	v_mov_b64_e32 v[92:93], 0
	v_mov_b64_e32 v[94:95], 0
	v_mov_b64_e32 v[96:97], 0
	v_mov_b64_e32 v[98:99], 0
	v_mov_b64_e32 v[100:101], 0
	v_mov_b64_e32 v[102:103], 0
	v_mov_b64_e32 v[104:105], 0
	v_mov_b64_e32 v[106:107], 0
	v_mov_b64_e32 v[108:109], 0
	v_mov_b64_e32 v[110:111], 0
	v_mov_b64_e32 v[112:113], 0
	v_mov_b64_e32 v[114:115], 0
	v_mov_b64_e32 v[116:117], 0
	v_mov_b64_e32 v[118:119], 0
	v_mov_b64_e32 v[120:121], 0
	v_mov_b64_e32 v[122:123], 0
	v_mov_b64_e32 v[124:125], 0
	v_mov_b64_e32 v[126:127], 0
	v_mov_b64_e32 v[128:129], 0
	s_cmp_lt_u32 s32, 0x100
	s_cbranch_scc0 .Lsprio_3
	s_setprio 1

.LBB0_955:
	v_mov_b32_e32 v125, 0
	s_andn2_b64 vcc, exec, s[20:21]
	v_mov_b32_e32 v124, v125
	v_mov_b32_e32 v123, v125
	v_mov_b32_e32 v122, v125
	v_mov_b32_e32 v129, v125
	v_mov_b32_e32 v128, v125
	v_mov_b32_e32 v127, v125
	v_mov_b32_e32 v126, v125
	v_mov_b32_e32 v113, v125
	v_mov_b32_e32 v112, v125
	v_mov_b32_e32 v111, v125
	v_mov_b32_e32 v110, v125
	v_mov_b32_e32 v109, v125
	v_mov_b32_e32 v108, v125
	v_mov_b32_e32 v107, v125
	v_mov_b32_e32 v106, v125
	v_mov_b32_e32 v97, v125
	v_mov_b32_e32 v96, v125
	v_mov_b32_e32 v95, v125
	v_mov_b32_e32 v94, v125
	v_mov_b32_e32 v93, v125
	v_mov_b32_e32 v92, v125
	v_mov_b32_e32 v91, v125
	v_mov_b32_e32 v90, v125
	v_mov_b32_e32 v81, v125
	v_mov_b32_e32 v80, v125
	v_mov_b32_e32 v79, v125
	v_mov_b32_e32 v78, v125
	v_mov_b32_e32 v77, v125
	v_mov_b32_e32 v76, v125
	v_mov_b32_e32 v75, v125
	v_mov_b32_e32 v74, v125
	v_mov_b32_e32 v121, v125
	v_mov_b32_e32 v120, v125
	v_mov_b32_e32 v119, v125
	v_mov_b32_e32 v118, v125
	v_mov_b32_e32 v117, v125
	v_mov_b32_e32 v116, v125
	v_mov_b32_e32 v115, v125
	v_mov_b32_e32 v114, v125
	v_mov_b32_e32 v105, v125
	v_mov_b32_e32 v104, v125
	v_mov_b32_e32 v103, v125
	v_mov_b32_e32 v102, v125
	v_mov_b32_e32 v101, v125
	v_mov_b32_e32 v100, v125
	v_mov_b32_e32 v99, v125
	v_mov_b32_e32 v98, v125
	v_mov_b32_e32 v89, v125
	v_mov_b32_e32 v88, v125
	v_mov_b32_e32 v87, v125
	v_mov_b32_e32 v86, v125
	v_mov_b32_e32 v85, v125
	v_mov_b32_e32 v84, v125
	v_mov_b32_e32 v83, v125
	v_mov_b32_e32 v82, v125
	v_mov_b32_e32 v73, v125
	v_mov_b32_e32 v72, v125
	v_mov_b32_e32 v71, v125
	v_mov_b32_e32 v70, v125
	v_mov_b32_e32 v69, v125
	v_mov_b32_e32 v68, v125
	v_mov_b32_e32 v67, v125
	v_mov_b32_e32 v66, v125
	v_mov_b32_e32 v65, v125
	v_mov_b32_e32 v64, v125
	v_mov_b32_e32 v63, v125
	v_mov_b32_e32 v62, v125
	v_mov_b32_e32 v61, v125
	v_mov_b32_e32 v60, v125
	v_mov_b32_e32 v59, v125
	v_mov_b32_e32 v58, v125
	v_mov_b32_e32 v49, v125
	v_mov_b32_e32 v48, v125
	v_mov_b32_e32 v47, v125
	v_mov_b32_e32 v46, v125
	v_mov_b32_e32 v45, v125
	v_mov_b32_e32 v44, v125
	v_mov_b32_e32 v43, v125
	v_mov_b32_e32 v42, v125
	v_mov_b32_e32 v33, v125
	v_mov_b32_e32 v32, v125
	v_mov_b32_e32 v31, v125
	v_mov_b32_e32 v30, v125
	v_mov_b32_e32 v29, v125
	v_mov_b32_e32 v28, v125
	v_mov_b32_e32 v27, v125
	v_mov_b32_e32 v26, v125
	v_mov_b32_e32 v17, v125
	v_mov_b32_e32 v16, v125
	v_mov_b32_e32 v15, v125
	v_mov_b32_e32 v14, v125
	v_mov_b32_e32 v13, v125
	v_mov_b32_e32 v12, v125
	v_mov_b32_e32 v11, v125
	v_mov_b32_e32 v10, v125
	v_mov_b32_e32 v57, v125
	v_mov_b32_e32 v56, v125
	v_mov_b32_e32 v55, v125
	v_mov_b32_e32 v54, v125
	v_mov_b32_e32 v53, v125
	v_mov_b32_e32 v52, v125
	v_mov_b32_e32 v51, v125
	v_mov_b32_e32 v50, v125
	v_mov_b32_e32 v41, v125
	v_mov_b32_e32 v40, v125
	v_mov_b32_e32 v39, v125
	v_mov_b32_e32 v38, v125
	v_mov_b32_e32 v37, v125
	v_mov_b32_e32 v36, v125
	v_mov_b32_e32 v35, v125
	v_mov_b32_e32 v34, v125
	v_mov_b32_e32 v25, v125
	v_mov_b32_e32 v24, v125
	v_mov_b32_e32 v23, v125
	v_mov_b32_e32 v22, v125
	v_mov_b32_e32 v21, v125
	v_mov_b32_e32 v20, v125
	v_mov_b32_e32 v19, v125
	v_mov_b32_e32 v18, v125
	v_mov_b32_e32 v9, v125
	v_mov_b32_e32 v8, v125
	v_mov_b32_e32 v7, v125
	v_mov_b32_e32 v6, v125
	v_mov_b32_e32 v5, v125
	v_mov_b32_e32 v4, v125
	v_mov_b32_e32 v3, v125
	v_mov_b32_e32 v2, v125
	s_cbranch_vccnz .LBB0_958
	s_add_u32 s36, s36, 0x80
	s_addc_u32 s37, s37, 0
	s_add_u32 s50, s40, 0x100
	s_addc_u32 s51, s41, 0
	s_mov_b32 s40, 0
	v_mov_b64_e32 v[2:3], 0
	v_mov_b64_e32 v[4:5], 0
	v_mov_b64_e32 v[6:7], 0
	v_mov_b64_e32 v[8:9], 0
	v_mov_b64_e32 v[10:11], 0
	v_mov_b64_e32 v[12:13], 0
	v_mov_b64_e32 v[14:15], 0
	v_mov_b64_e32 v[16:17], 0
	v_mov_b64_e32 v[18:19], 0
	v_mov_b64_e32 v[20:21], 0
	v_mov_b64_e32 v[22:23], 0
	v_mov_b64_e32 v[24:25], 0
	v_mov_b64_e32 v[26:27], 0
	v_mov_b64_e32 v[28:29], 0
	v_mov_b64_e32 v[30:31], 0
	v_mov_b64_e32 v[32:33], 0
	v_mov_b64_e32 v[34:35], 0
	v_mov_b64_e32 v[36:37], 0
	v_mov_b64_e32 v[38:39], 0
	v_mov_b64_e32 v[40:41], 0
	v_mov_b64_e32 v[42:43], 0
	v_mov_b64_e32 v[44:45], 0
	v_mov_b64_e32 v[46:47], 0
	v_mov_b64_e32 v[48:49], 0
	v_mov_b64_e32 v[50:51], 0
	v_mov_b64_e32 v[52:53], 0
	v_mov_b64_e32 v[54:55], 0
	v_mov_b64_e32 v[56:57], 0
	v_mov_b64_e32 v[58:59], 0
	v_mov_b64_e32 v[60:61], 0
	v_mov_b64_e32 v[62:63], 0
	v_mov_b64_e32 v[64:65], 0
	v_mov_b64_e32 v[66:67], 0
	v_mov_b64_e32 v[68:69], 0
	v_mov_b64_e32 v[70:71], 0
	v_mov_b64_e32 v[72:73], 0
	v_mov_b64_e32 v[74:75], 0
	v_mov_b64_e32 v[76:77], 0
	v_mov_b64_e32 v[78:79], 0
	v_mov_b64_e32 v[80:81], 0
	v_mov_b64_e32 v[82:83], 0
	v_mov_b64_e32 v[84:85], 0
	v_mov_b64_e32 v[86:87], 0
	v_mov_b64_e32 v[88:89], 0
	v_mov_b64_e32 v[90:91], 0
	v_mov_b64_e32 v[92:93], 0
	v_mov_b64_e32 v[94:95], 0
	v_mov_b64_e32 v[96:97], 0
	v_mov_b64_e32 v[98:99], 0
	v_mov_b64_e32 v[100:101], 0
	v_mov_b64_e32 v[102:103], 0
	v_mov_b64_e32 v[104:105], 0
	v_mov_b64_e32 v[106:107], 0
	v_mov_b64_e32 v[108:109], 0
	v_mov_b64_e32 v[110:111], 0
	v_mov_b64_e32 v[112:113], 0
	v_mov_b64_e32 v[114:115], 0
	v_mov_b64_e32 v[116:117], 0
	v_mov_b64_e32 v[118:119], 0
	v_mov_b64_e32 v[120:121], 0
	v_mov_b64_e32 v[122:123], 0
	v_mov_b64_e32 v[124:125], 0
	v_mov_b64_e32 v[126:127], 0
	v_mov_b64_e32 v[128:129], 0
	s_cmp_lt_u32 s32, 0x100
	s_cbranch_scc0 .Lsprio_4
	s_setprio 1

.LBB0_985:
	s_ashr_i32 s21, s20, 31
	s_lshl_b64 s[18:19], s[20:21], 19
	s_add_u32 s34, s29, s18
	s_addc_u32 s35, s44, s19
	s_and_b64 s[18:19], s[40:41], exec
	s_cselect_b32 s3, s35, s13
	s_cselect_b32 s16, s34, s12
	s_ashr_i32 s15, s14, 31
	s_lshl_b64 s[18:19], s[14:15], 19
	s_add_u32 s42, s45, s18
	s_addc_u32 s43, s46, s19
	s_and_b64 s[18:19], s[40:41], exec
	s_cselect_b32 s15, s43, s31
	s_cselect_b32 s18, s42, s30
	s_add_u32 s12, s12, 0x40080
	s_addc_u32 s13, s13, 0
	s_add_u32 s19, s30, 0x100
	s_addc_u32 s21, s31, 0
	s_mov_b32 s24, -2
	v_mov_b64_e32 v[2:3], 0
	v_mov_b64_e32 v[4:5], 0
	v_mov_b64_e32 v[6:7], 0
	v_mov_b64_e32 v[8:9], 0
	v_mov_b64_e32 v[10:11], 0
	v_mov_b64_e32 v[12:13], 0
	v_mov_b64_e32 v[14:15], 0
	v_mov_b64_e32 v[16:17], 0
	v_mov_b64_e32 v[18:19], 0
	v_mov_b64_e32 v[20:21], 0
	v_mov_b64_e32 v[22:23], 0
	v_mov_b64_e32 v[24:25], 0
	v_mov_b64_e32 v[26:27], 0
	v_mov_b64_e32 v[28:29], 0
	v_mov_b64_e32 v[30:31], 0
	v_mov_b64_e32 v[32:33], 0
	v_mov_b64_e32 v[34:35], 0
	v_mov_b64_e32 v[36:37], 0
	v_mov_b64_e32 v[38:39], 0
	v_mov_b64_e32 v[40:41], 0
	v_mov_b64_e32 v[42:43], 0
	v_mov_b64_e32 v[44:45], 0
	v_mov_b64_e32 v[46:47], 0
	v_mov_b64_e32 v[48:49], 0
	v_mov_b64_e32 v[50:51], 0
	v_mov_b64_e32 v[52:53], 0
	v_mov_b64_e32 v[54:55], 0
	v_mov_b64_e32 v[56:57], 0
	v_mov_b64_e32 v[58:59], 0
	v_mov_b64_e32 v[60:61], 0
	v_mov_b64_e32 v[62:63], 0
	v_mov_b64_e32 v[64:65], 0
	v_mov_b64_e32 v[66:67], 0
	v_mov_b64_e32 v[68:69], 0
	v_mov_b64_e32 v[70:71], 0
	v_mov_b64_e32 v[72:73], 0
	v_mov_b64_e32 v[74:75], 0
	v_mov_b64_e32 v[76:77], 0
	v_mov_b64_e32 v[78:79], 0
	v_mov_b64_e32 v[80:81], 0
	v_mov_b64_e32 v[82:83], 0
	v_mov_b64_e32 v[84:85], 0
	v_mov_b64_e32 v[86:87], 0
	v_mov_b64_e32 v[88:89], 0
	v_mov_b64_e32 v[90:91], 0
	v_mov_b64_e32 v[92:93], 0
	v_mov_b64_e32 v[94:95], 0
	v_mov_b64_e32 v[96:97], 0
	v_mov_b64_e32 v[98:99], 0
	v_mov_b64_e32 v[100:101], 0
	v_mov_b64_e32 v[102:103], 0
	v_mov_b64_e32 v[104:105], 0
	v_mov_b64_e32 v[106:107], 0
	v_mov_b64_e32 v[108:109], 0
	v_mov_b64_e32 v[110:111], 0
	v_mov_b64_e32 v[112:113], 0
	v_mov_b64_e32 v[114:115], 0
	v_mov_b64_e32 v[116:117], 0
	v_mov_b64_e32 v[118:119], 0
	v_mov_b64_e32 v[120:121], 0
	v_mov_b64_e32 v[122:123], 0
	v_mov_b64_e32 v[124:125], 0
	v_mov_b64_e32 v[126:127], 0
	v_mov_b64_e32 v[128:129], 0
	s_cmp_lt_u32 s32, 0x100
	s_cbranch_scc0 .Lsprio_5
	s_setprio 1
